# L2 code warm-up window 64KB (two 1KB loads per non-last workgroup at each seam)
# baseline (speedup 1.0000x reference)
; __device__ __forceinline__ int lane_id_() { int l; asm volatile("v_mbcnt_lo_u32_b32 %0, -1, 0\n\tv_mbcnt_hi_u32_b32 %0, -1, %0" : "=v"(l)); return l; }
; __device__ __forceinline__ unsigned xb_ld(unsigned* p)              { return __hip_atomic_load(p, __ATOMIC_RELAXED, __HIP_MEMORY_SCOPE_AGENT); }
; __device__ __forceinline__ unsigned xb_add(unsigned* p, unsigned v) { return __hip_atomic_fetch_add(p, v, __ATOMIC_RELAXED, __HIP_MEMORY_SCOPE_AGENT); }
; #define XB_SPIN(cond, bar) do { unsigned _sp = 0; while (cond) { __builtin_amdgcn_s_sleep(1); \
;     if ((++_sp & 255u) == 0u) { if (xb_ld(&(bar)[XB_TMO])) break; if (_sp > XB_SPIN_CAP) { atomicAdd(&(bar)[XB_TMO], 1u); break; } } } } while (0)
; __device__ __forceinline__ void xcd_barrier(const XcdBarrier& b, int wave_s) {
;     ...
;     if (wave_s == 0 && lane_id_() == 0) {
;         unsigned* bar = b.bar;
;         __builtin_amdgcn_s_waitcnt(0);
;         unsigned nloc = b.st[0], nx = b.st[1];
;         if (nloc == 0u) { xcd_barrier_complete(bar, b.x, nloc, nx); b.st[0] = nloc; b.st[1] = nx; }
;         const unsigned old = xb_add(&bar[XB_XSUB(b.x)], 1u);
;         const unsigned gen = old / nloc;
;         if (old + 1u == (gen + 1u) * nloc) {
;             __builtin_amdgcn_fence(__ATOMIC_RELEASE, "agent");
;             asm volatile("s_waitcnt vmcnt(0)" ::: "memory");
;             const unsigned og = xb_add(&bar[XB_TOP], 1u);
;             const unsigned tg = og / nx;
;             if (og + 1u == (tg + 1u) * nx) xb_add(&bar[XB_TOPGEN], 1u);
;             else XB_SPIN(xb_ld(&bar[XB_TOPGEN]) == tg, bar);
;             __builtin_amdgcn_fence(__ATOMIC_ACQUIRE, "agent");
;             xb_add(&bar[XB_XGEN(b.x)], 1u);
;             asm volatile("s_waitcnt vmcnt(0)" ::: "memory");
;         } else {
;             XB_SPIN(xb_ld(&bar[XB_XGEN(b.x)]) == gen, bar);
.Llw_S1:
	v_mov_b32_e32 v1, s98
	s_getpc_b64 s[98:99]
	s_lshr_b32 s100, s33, 3
	s_and_b32 s100, s100, 31
	s_lshl_b32 s100, s100, 11
	s_add_u32 s98, s98, s100
	s_addc_u32 s99, s99, 0
	s_mov_b64 exec, -1
	v_mbcnt_lo_u32_b32 v4, -1, 0
	v_mbcnt_hi_u32_b32 v4, -1, v4
	v_lshlrev_b32_e32 v4, 4, v4
	global_load_dwordx4 v[6:9], v4, s[98:99]
	global_load_dwordx4 v[6:9], v4, s[98:99] offset:1024
	s_mov_b64 exec, 1
	v_readfirstlane_b32 s98, v1
	s_nop 3

; __device__ __forceinline__ int lane_id_() { int l; asm volatile("v_mbcnt_lo_u32_b32 %0, -1, 0\n\tv_mbcnt_hi_u32_b32 %0, -1, %0" : "=v"(l)); return l; }
; __device__ __forceinline__ unsigned xb_ld(unsigned* p)              { return __hip_atomic_load(p, __ATOMIC_RELAXED, __HIP_MEMORY_SCOPE_AGENT); }
; __device__ __forceinline__ unsigned xb_add(unsigned* p, unsigned v) { return __hip_atomic_fetch_add(p, v, __ATOMIC_RELAXED, __HIP_MEMORY_SCOPE_AGENT); }
; #define XB_SPIN(cond, bar) do { unsigned _sp = 0; while (cond) { __builtin_amdgcn_s_sleep(1); \
;     if ((++_sp & 255u) == 0u) { if (xb_ld(&(bar)[XB_TMO])) break; if (_sp > XB_SPIN_CAP) { atomicAdd(&(bar)[XB_TMO], 1u); break; } } } } while (0)
; __device__ __forceinline__ void xcd_barrier(const XcdBarrier& b, int wave_s) {
;     ...
;     if (wave_s == 0 && lane_id_() == 0) {
;         unsigned* bar = b.bar;
;         __builtin_amdgcn_s_waitcnt(0);
;         unsigned nloc = b.st[0], nx = b.st[1];
;         if (nloc == 0u) { xcd_barrier_complete(bar, b.x, nloc, nx); b.st[0] = nloc; b.st[1] = nx; }
;         const unsigned old = xb_add(&bar[XB_XSUB(b.x)], 1u);
;         const unsigned gen = old / nloc;
;         if (old + 1u == (gen + 1u) * nloc) {
;             __builtin_amdgcn_fence(__ATOMIC_RELEASE, "agent");
;             asm volatile("s_waitcnt vmcnt(0)" ::: "memory");
;             const unsigned og = xb_add(&bar[XB_TOP], 1u);
;             const unsigned tg = og / nx;
;             if (og + 1u == (tg + 1u) * nx) xb_add(&bar[XB_TOPGEN], 1u);
;             else XB_SPIN(xb_ld(&bar[XB_TOPGEN]) == tg, bar);
;             __builtin_amdgcn_fence(__ATOMIC_ACQUIRE, "agent");
;             xb_add(&bar[XB_XGEN(b.x)], 1u);
;             asm volatile("s_waitcnt vmcnt(0)" ::: "memory");
;         } else {
;             XB_SPIN(xb_ld(&bar[XB_XGEN(b.x)]) == gen, bar);
.Llw_S4:
	v_mov_b32_e32 v1, s98
	s_getpc_b64 s[98:99]
	s_lshr_b32 s100, s33, 3
	s_and_b32 s100, s100, 31
	s_lshl_b32 s100, s100, 11
	s_add_u32 s98, s98, s100
	s_addc_u32 s99, s99, 0
	s_mov_b64 exec, -1
	v_mbcnt_lo_u32_b32 v4, -1, 0
	v_mbcnt_hi_u32_b32 v4, -1, v4
	v_lshlrev_b32_e32 v4, 4, v4
	global_load_dwordx4 v[6:9], v4, s[98:99]
	global_load_dwordx4 v[6:9], v4, s[98:99] offset:1024
	s_mov_b64 exec, 1
	v_readfirstlane_b32 s98, v1
	s_nop 3
	s_mov_b32 s99, 0
